# scan stage Y: side-operand (P1/P3) reads issued after the state-update MFMAs
# baseline (speedup 1.0000x reference)
.Lpq0_end:
	s_waitcnt lgkmcnt(0)
	s_barrier
	v_add_u32_e32 v200, v146, v145
	v_add_u32_e32 v112, v156, v163
	ds_read_b128 v[48:51], v180
	ds_read_b128 v[52:55], v112 offset:62976
	ds_read_b128 v[56:59], v112 offset:64256
	v_sub_u32_e32 v113, v164, v143
	v_mad_u32_u24 v113, v145, 5, v113
	v_add_u32_e32 v113, 0x18d00, v113
	ds_read_b128 v[88:91], v113
	ds_read_b128 v[92:95], v113 offset:64
	v_mul_u32_u24_e32 v114, 5, v145
	v_sub_u32_e32 v114, v143, v114
	v_mul_i32_i24_e32 v114, 0x47, v114
	v_ashrrev_i32_e32 v114, 1, v114
	v_add_u32_e32 v114, v181, v114
	s_waitcnt lgkmcnt(2)
	v_mfma_f32_16x16x32_bf16 v[14:17], v[52:55], v[48:51], v[14:17]
	v_mfma_f32_16x16x32_bf16 v[18:21], v[56:59], v[48:51], v[18:21]
	s_waitcnt lgkmcnt(0)
	s_and_saveexec_b64 s[2:3], s[56:57]
	s_cbranch_execz .Lsy0_r1
	ds_read_b128 v[62:65], v175
	ds_read_b128 v[66:69], v200

.Lsy0_r2:
	s_or_b64 exec, exec, s[2:3]
	s_nop 3
	v_pk_mul_f32 v[14:15], v[14:15], v[88:89]
	v_pk_mul_f32 v[16:17], v[16:17], v[90:91]
	v_pk_mul_f32 v[18:19], v[18:19], v[92:93]
	v_pk_mul_f32 v[20:21], v[20:21], v[94:95]
	v_cvt_pk_bf16_f32 v116, v14, v15
	v_cvt_pk_bf16_f32 v117, v16, v17
	v_cvt_pk_bf16_f32 v118, v18, v19
	v_cvt_pk_bf16_f32 v119, v20, v21
	ds_write_b64 v114, v[116:117]
	ds_write_b64 v114, v[118:119] offset:32
	s_and_saveexec_b64 s[2:3], s[56:57]
	s_cbranch_execz .Lsy0_m1
	s_waitcnt lgkmcnt(2)
	v_mfma_f32_16x16x32_bf16 v[22:25], v[62:65], v[66:69], v[22:25]
.Lsy0_m1:
	s_or_b64 exec, exec, s[2:3]
	s_and_saveexec_b64 s[2:3], s[46:47]
	s_cbranch_execz .Lsy0_m2
	s_waitcnt lgkmcnt(4)
	v_mfma_f32_16x16x32_bf16 v[22:25], v[70:73], v[74:77], 0
	s_waitcnt lgkmcnt(2)
	v_mfma_f32_16x16x32_bf16 v[22:25], v[78:81], v[82:85], v[22:25]
.Lsy0_m2:
	s_or_b64 exec, exec, s[2:3]
	s_nop 7
	s_nop 1
	s_and_saveexec_b64 s[2:3], s[56:57]
	s_cbranch_execz .Lsy0_w1
	ds_write_b128 v179, v[22:25]

.Lpq1_end:
	s_waitcnt lgkmcnt(0)
	s_barrier
	s_and_b64 s[24:25], s[46:47], s[2:3]
	ds_read_b128 v[48:51], v180 offset:5120
	ds_read_b128 v[52:55], v170 offset:5120
	ds_read_b128 v[56:59], v170 offset:6400
	v_sub_u32_e32 v113, v164, v143
	v_mad_u32_u24 v113, v145, 5, v113
	v_add_u32_e32 v113, 0x18e00, v113
	ds_read_b128 v[88:91], v113
	ds_read_b128 v[92:95], v113 offset:64
	v_mul_u32_u24_e32 v114, 5, v145
	v_sub_u32_e32 v114, v143, v114
	v_mul_i32_i24_e32 v114, 0x47, v114
	v_ashrrev_i32_e32 v114, 1, v114
	v_add_u32_e32 v114, v181, v114
	s_waitcnt lgkmcnt(2)
	v_mfma_f32_16x16x32_bf16 v[14:17], v[52:55], v[48:51], v[14:17]
	v_mfma_f32_16x16x32_bf16 v[18:21], v[56:59], v[48:51], v[18:21]
	s_waitcnt lgkmcnt(0)
	s_and_saveexec_b64 s[74:75], s[56:57]
	s_cbranch_execz .Lsy1_r1
	ds_read_b128 v[62:65], v175 offset:5120
	ds_read_b128 v[66:69], v200 offset:1280

.Lsy1_r2:
	s_or_b64 exec, exec, s[74:75]
	s_nop 3
	v_pk_mul_f32 v[14:15], v[14:15], v[88:89]
	v_pk_mul_f32 v[16:17], v[16:17], v[90:91]
	v_pk_mul_f32 v[18:19], v[18:19], v[92:93]
	v_pk_mul_f32 v[20:21], v[20:21], v[94:95]
	v_cvt_pk_bf16_f32 v116, v14, v15
	v_cvt_pk_bf16_f32 v117, v16, v17
	v_cvt_pk_bf16_f32 v118, v18, v19
	v_cvt_pk_bf16_f32 v119, v20, v21
	ds_write_b64 v114, v[116:117]
	ds_write_b64 v114, v[118:119] offset:32
	s_and_saveexec_b64 s[74:75], s[56:57]
	s_cbranch_execz .Lsy1_m1
	s_waitcnt lgkmcnt(2)
	v_mfma_f32_16x16x32_bf16 v[22:25], v[62:65], v[66:69], v[22:25]
.Lsy1_m1:
	s_or_b64 exec, exec, s[74:75]
	s_and_saveexec_b64 s[74:75], s[24:25]
	s_cbranch_execz .Lsy1_m2
	s_waitcnt lgkmcnt(4)
	v_mfma_f32_16x16x32_bf16 v[22:25], v[70:73], v[74:77], 0
	s_waitcnt lgkmcnt(2)
	v_mfma_f32_16x16x32_bf16 v[22:25], v[78:81], v[82:85], v[22:25]
.Lsy1_m2:
	s_or_b64 exec, exec, s[74:75]
	s_nop 7
	s_nop 1
	s_and_saveexec_b64 s[74:75], s[56:57]
	s_cbranch_execz .Lsy1_w1
	ds_write_b128 v179, v[22:25] offset:4096
